# waves 1-4 touch the next phase weight tile (first 4 K-tiles) into L2 behind each dataflow sync
# baseline (speedup 1.0000x reference)
; #define GSYNC() do { for (int r_ = 0; r_ < REP_SYNC; ++r_) xcd_barrier(bar); } while (0)
; __global__ void __launch_bounds__(NWAVES * 64, 2) mk_fwd(Args a) {
;     ...
;         GSYNC();
;         {
;             pg8::Gemm g{ACT, (const bf16u*)(wl + WL_D), NTOK, DMOD, DFF}; int bxp = bx; asm volatile("" : "+s"(bxp)); pg8::StaticOrder S; S.init(NTOK, DMOD, G, bxp);
;             pg8::EpiResid E{XB, ssqA};
;             pg8::gemm_phase<pg8::EpiResid, pg8::StaticOrder, true, true>(L, g, S, E);
;         }
;         GSYNC();
;     }
.Lgb_arm_skip:
	s_cmp_eq_u32 s2, 4
	s_mov_b32 s92, s2
	s_waitcnt lgkmcnt(0)
	s_waitcnt vmcnt(0)
	s_barrier
	s_cbranch_scc1 .LBB0_759

; __device__ __forceinline__ unsigned xb_add(unsigned* p, unsigned v) { return __hip_atomic_fetch_add(p, v, __ATOMIC_RELAXED, __HIP_MEMORY_SCOPE_AGENT); }
; __device__ __forceinline__ void xcd_barrier(const XcdBarrier& b) {
;     asm volatile("s_waitcnt vmcnt(0)" ::: "memory");
;     __syncthreads();
;     if (threadIdx.x == 0) {
;         unsigned* bar = b.bar;
;         __builtin_amdgcn_s_waitcnt(0);
;         unsigned nloc = b.st[0], nx = b.st[1];
;         if (nloc == 0u) { xcd_barrier_complete(bar, b.x, nloc, nx); b.st[0] = nloc; b.st[1] = nx; }
;         const unsigned old = xb_add(&bar[XB_XSUB(b.x)], 1u);
;         const unsigned gen = old / nloc;
;         if (old + 1u == (gen + 1u) * nloc) {
.LBB0_351:
	s_waitcnt vmcnt(0)
	s_barrier
	s_cmp_lg_u32 s98, 0
	s_cbranch_scc0 .Lpf_skip_403
	v_readlane_b32 s101, v253, 38
	v_readlane_b32 s12, v255, 45
	v_readlane_b32 s13, v255, 46
	s_nop 3
	s_sub_u32 s101, s101, 1
	s_cmp_gt_u32 s101, 3
	s_cbranch_scc1 .Lpf_skip_403
	v_and_b32_e32 v140, 63, v244
	v_lshl_add_u32 v140, s101, 6, v140
	v_mul_u32_u24_e32 v140, 0x800, v140
	v_readlane_b32 s101, v253, 1
	s_add_u32 s12, s12, 0x1000000
	s_addc_u32 s13, s13, 0
	s_nop 1
	s_lshr_b32 s101, s101, 6
	s_mul_i32 s101, s101, 0x80000
	s_add_u32 s12, s12, s101
	s_addc_u32 s13, s13, 0
	global_load_dword v141, v140, s[12:13]
	global_load_dword v141, v140, s[12:13] offset:64
	global_load_dword v141, v140, s[12:13] offset:128
	global_load_dword v141, v140, s[12:13] offset:192
	global_load_dword v141, v140, s[12:13] offset:256
	global_load_dword v141, v140, s[12:13] offset:320
	global_load_dword v141, v140, s[12:13] offset:384
	global_load_dword v141, v140, s[12:13] offset:448
.Lpf_skip_403:
	s_mov_b64 s[2:3], exec
	v_readlane_b32 s12, v253, 36
	v_readlane_b32 s13, v253, 37
	s_and_b64 s[12:13], s[2:3], s[12:13]
	s_mov_b64 exec, s[12:13]
	s_cbranch_execz .LBB0_403
	s_cmp_lg_u32 s98, 0
	s_cbranch_scc0 .Lgb_full_403
	v_readlane_b32 s4, v253, 0
	v_readlane_b32 s1, v253, 1
	v_readlane_b32 s12, v253, 56
	v_readlane_b32 s13, v253, 57
	s_nop 3
	s_lshr_b32 s16, s4, 6
	s_lshl_b32 s16, s16, 4
	s_and_b32 s17, s4, 7
	s_add_i32 s18, s16, s17
	s_sub_i32 s19, s16, s17
	s_add_i32 s19, s19, 15
	s_lshr_b32 s20, s4, 2
	s_lshl_b32 s18, s18, 6
	s_lshl_b32 s19, s19, 6
	s_lshl_b32 s20, s20, 6
	s_add_i32 s18, s18, 0x5f00
	s_add_i32 s19, s19, 0x5f00
	s_add_i32 s20, s20, 0x5f00
	v_mov_b32_e32 v2, s18
	v_mov_b32_e32 v3, s19
	v_mov_b32_e32 v4, s20
	s_and_b32 s16, s1, 7
	s_lshl_b32 s16, s16, 3
	s_bfe_u32 s17, s1, 0x30003
	s_add_i32 s16, s16, s17
	s_lshl_b32 s16, s16, 6
	s_add_i32 s16, s16, 0x5f00
	v_mov_b32_e32 v5, s16
	s_add_i32 s21, s92, 1
	s_mul_i32 s21, s21, 12
	s_mov_b32 s1, 0
	global_atomic_add v2, v234, s[12:13]
	global_atomic_add v3, v234, s[12:13]
	global_atomic_add v4, v234, s[12:13]

;     __host__ __device__ bool next(int i, Unit& u) const {
;         const long L = (long)i * G + c; if (L >= nwg) return false;
;         int wgid = (int)L; { const int q = nwg / NXCD, r = nwg % NXCD, xcd = wgid % NXCD, off = wgid / NXCD; wgid = (xcd < r ? xcd * (q + 1) : r * (q + 1) + (xcd - r) * q) + off; }
;         const int nig = WGM * nN, gid = wgid / nig, fm = gid * WGM, gsz = (nM - fm) < WGM ? (nM - fm) : WGM;
;         u.pm = fm + ((wgid % nig) % gsz); u.pn = (wgid % nig) / gsz; return true;
; __device__ __forceinline__ void xcd_barrier(const XcdBarrier& b) {
;     ...
;             __builtin_amdgcn_fence(__ATOMIC_ACQUIRE, "agent");
;             asm volatile("s_waitcnt vmcnt(0)" ::: "memory");
;         }
;     }
;     __syncthreads();
; }
.LBB0_403:
	s_or_b64 exec, exec, s[2:3]
	s_mov_b32 s1, s69
	s_waitcnt lgkmcnt(0)
	s_waitcnt vmcnt(0)
	s_barrier
	v_mov_b32_e32 v0, v244
	s_cmpk_lt_i32 s1, 0x100
	s_cselect_b64 s[2:3], -1, 0
	s_cmpk_gt_i32 s1, 0xff
	v_readfirstlane_b32 s4, v0
	s_cbranch_scc1 .LBB0_409
	s_ashr_i32 s12, s1, 31
	s_lshr_b32 s12, s12, 29
	s_add_i32 s12, s1, s12
	s_and_b32 s13, s12, -8
	s_sub_i32 s13, s1, s13
	s_cmp_gt_i32 s13, -1
	s_mov_b64 s[16:17], -1
	s_cbranch_scc0 .LBB0_406
	s_lshl_b32 s18, s13, 5
	s_mov_b64 s[16:17], 0

; __device__ __forceinline__ unsigned xb_add(unsigned* p, unsigned v) { return __hip_atomic_fetch_add(p, v, __ATOMIC_RELAXED, __HIP_MEMORY_SCOPE_AGENT); }
; __device__ __forceinline__ void xcd_barrier(const XcdBarrier& b) {
;     asm volatile("s_waitcnt vmcnt(0)" ::: "memory");
;     __syncthreads();
;     if (threadIdx.x == 0) {
;         unsigned* bar = b.bar;
;         __builtin_amdgcn_s_waitcnt(0);
;         unsigned nloc = b.st[0], nx = b.st[1];
;         if (nloc == 0u) { xcd_barrier_complete(bar, b.x, nloc, nx); b.st[0] = nloc; b.st[1] = nx; }
;         const unsigned old = xb_add(&bar[XB_XSUB(b.x)], 1u);
;         const unsigned gen = old / nloc;
;         if (old + 1u == (gen + 1u) * nloc) {
.LBB0_441:
	s_waitcnt vmcnt(0)
	s_barrier
	s_cmp_lg_u32 s98, 0
	s_cbranch_scc0 .Lpf_skip_493
	v_readlane_b32 s101, v253, 38
	v_readlane_b32 s12, v255, 45
	v_readlane_b32 s13, v255, 46
	s_nop 3
	s_sub_u32 s101, s101, 1
	s_cmp_gt_u32 s101, 3
	s_cbranch_scc1 .Lpf_skip_493
	v_and_b32_e32 v140, 63, v244
	v_lshl_add_u32 v140, s101, 6, v140
	v_mul_u32_u24_e32 v140, 0x800, v140
	v_readlane_b32 s101, v253, 1
	s_add_u32 s12, s12, 0x1400000
	s_addc_u32 s13, s13, 0
	s_nop 1
	s_lshr_b32 s101, s101, 6
	s_mul_i32 s101, s101, 0x80000
	s_add_u32 s12, s12, s101
	s_addc_u32 s13, s13, 0
	global_load_dword v141, v140, s[12:13]
	global_load_dword v141, v140, s[12:13] offset:64
	global_load_dword v141, v140, s[12:13] offset:128
	global_load_dword v141, v140, s[12:13] offset:192
	global_load_dword v141, v140, s[12:13] offset:256
	global_load_dword v141, v140, s[12:13] offset:320
	global_load_dword v141, v140, s[12:13] offset:384
	global_load_dword v141, v140, s[12:13] offset:448
.Lpf_skip_493:
	s_mov_b64 s[2:3], exec
	v_readlane_b32 s12, v253, 36
	v_readlane_b32 s13, v253, 37
	s_and_b64 s[12:13], s[2:3], s[12:13]
	s_mov_b64 exec, s[12:13]
	s_cbranch_execz .LBB0_493
	s_cmp_lg_u32 s98, 0
	s_cbranch_scc0 .Lgb_full_493
	v_readlane_b32 s4, v253, 1
	v_readlane_b32 s12, v253, 56
	v_readlane_b32 s13, v253, 57
	s_add_i32 s99, s99, 4
	s_nop 2
	s_and_b32 s4, s4, 63
	s_lshl_b32 s4, s4, 7
	s_add_i32 s4, s4, 0x3e00
	v_mov_b32_e32 v2, s4
	s_mov_b32 s1, 0
	s_nop 1
	global_atomic_add v5, v2, v234, s[12:13] sc0
	v_mov_b32_e32 v4, 0x5e00
	global_atomic_add v4, v234, s[12:13]
	s_waitcnt vmcnt(1)
	v_readfirstlane_b32 s4, v5
	s_nop 3
	s_add_i32 s4, s4, 1
	s_cmp_ge_u32 s4, s99
	s_cbranch_scc1 .Lgb_grp_ok_493

;     __host__ __device__ bool next(int i, Unit& u) const {
;         const long L = (long)i * G + c; if (L >= nwg) return false;
;         int wgid = (int)L; { const int q = nwg / NXCD, r = nwg % NXCD, xcd = wgid % NXCD, off = wgid / NXCD; wgid = (xcd < r ? xcd * (q + 1) : r * (q + 1) + (xcd - r) * q) + off; }
;         const int nig = WGM * nN, gid = wgid / nig, fm = gid * WGM, gsz = (nM - fm) < WGM ? (nM - fm) : WGM;
;         u.pm = fm + ((wgid % nig) % gsz); u.pn = (wgid % nig) / gsz; return true;
; __device__ __forceinline__ void xcd_barrier(const XcdBarrier& b) {
;     ...
;             __builtin_amdgcn_fence(__ATOMIC_ACQUIRE, "agent");
;             asm volatile("s_waitcnt vmcnt(0)" ::: "memory");
;         }
;     }
;     __syncthreads();
; }
.LBB0_493:
	s_or_b64 exec, exec, s[2:3]
	s_mov_b32 s1, s69
	s_waitcnt lgkmcnt(0)
	v_mov_b32_e32 v2, v244
	s_waitcnt vmcnt(0)
	s_barrier
	s_cmpk_lt_i32 s1, 0x100
	v_readfirstlane_b32 s12, v2
	s_cbranch_scc0 .LBB0_517
	s_ashr_i32 s13, s1, 31
	s_lshr_b32 s2, s13, 29
	s_add_i32 s17, s1, s2
	s_and_b32 s2, s17, -8
	s_sub_i32 s4, s1, s2
	s_cmp_gt_i32 s4, -1
	s_mov_b64 s[2:3], -1
	s_cbranch_scc0 .LBB0_496
	s_lshl_b32 s16, s4, 5
	s_mov_b64 s[2:3], 0

; __device__ __forceinline__ unsigned xb_add(unsigned* p, unsigned v) { return __hip_atomic_fetch_add(p, v, __ATOMIC_RELAXED, __HIP_MEMORY_SCOPE_AGENT); }
; __device__ __forceinline__ void xcd_barrier(const XcdBarrier& b) {
;     asm volatile("s_waitcnt vmcnt(0)" ::: "memory");
;     __syncthreads();
;     if (threadIdx.x == 0) {
;         unsigned* bar = b.bar;
;         __builtin_amdgcn_s_waitcnt(0);
;         unsigned nloc = b.st[0], nx = b.st[1];
;         if (nloc == 0u) { xcd_barrier_complete(bar, b.x, nloc, nx); b.st[0] = nloc; b.st[1] = nx; }
;         const unsigned old = xb_add(&bar[XB_XSUB(b.x)], 1u);
;         const unsigned gen = old / nloc;
;         if (old + 1u == (gen + 1u) * nloc) {
.LBB0_517:
	s_waitcnt vmcnt(0)
	s_barrier
	s_cmp_lg_u32 s98, 0
	s_cbranch_scc0 .Lpf_skip_569
	v_readlane_b32 s101, v253, 38
	v_readlane_b32 s12, v255, 45
	v_readlane_b32 s13, v255, 46
	s_nop 3
	s_sub_u32 s101, s101, 1
	s_cmp_gt_u32 s101, 3
	s_cbranch_scc1 .Lpf_skip_569
	v_and_b32_e32 v140, 63, v244
	v_lshl_add_u32 v140, s101, 6, v140
	v_mul_u32_u24_e32 v140, 0x800, v140
	v_readlane_b32 s101, v253, 1
	s_add_u32 s12, s12, 0x1600000
	s_addc_u32 s13, s13, 0
	s_nop 1
	s_lshr_b32 s101, s101, 6
	s_mul_i32 s101, s101, 0x80000
	s_add_u32 s12, s12, s101
	s_addc_u32 s13, s13, 0
	global_load_dword v141, v140, s[12:13]
	global_load_dword v141, v140, s[12:13] offset:64
	global_load_dword v141, v140, s[12:13] offset:128
	global_load_dword v141, v140, s[12:13] offset:192
	global_load_dword v141, v140, s[12:13] offset:256
	global_load_dword v141, v140, s[12:13] offset:320
	global_load_dword v141, v140, s[12:13] offset:384
	global_load_dword v141, v140, s[12:13] offset:448
.Lpf_skip_569:
	s_mov_b64 s[2:3], exec
	v_readlane_b32 s12, v253, 36
	v_readlane_b32 s13, v253, 37
	s_and_b64 s[12:13], s[2:3], s[12:13]
	s_mov_b64 exec, s[12:13]
	s_cbranch_execz .LBB0_569
	s_cmp_lg_u32 s98, 0
	s_cbranch_scc0 .Lgb_full_569
	v_readlane_b32 s4, v253, 1
	v_readlane_b32 s12, v253, 56
	v_readlane_b32 s13, v253, 57
	s_add_i32 s99, s99, 4
	s_nop 2
	s_and_b32 s4, s4, 63
	s_lshl_b32 s4, s4, 7
	s_add_i32 s4, s4, 0x3e00
	v_mov_b32_e32 v2, s4
	s_mov_b32 s1, 0
	s_nop 1
	global_atomic_add v5, v2, v234, s[12:13] sc0
	v_mov_b32_e32 v7, 0x5e00
	global_load_dword v6, v7, s[12:13] sc1
	s_waitcnt vmcnt(1)
	v_readfirstlane_b32 s4, v5
	s_nop 3
	s_add_i32 s4, s4, 1
	s_cmp_ge_u32 s4, s99
	s_cbranch_scc1 .Lgb_grp_ok_569

;     __host__ __device__ bool next(int i, Unit& u) const {
;         const long L = (long)i * G + c; if (L >= nwg) return false;
;         int wgid = (int)L; { const int q = nwg / NXCD, r = nwg % NXCD, xcd = wgid % NXCD, off = wgid / NXCD; wgid = (xcd < r ? xcd * (q + 1) : r * (q + 1) + (xcd - r) * q) + off; }
;         const int nig = WGM * nN, gid = wgid / nig, fm = gid * WGM, gsz = (nM - fm) < WGM ? (nM - fm) : WGM;
;         u.pm = fm + ((wgid % nig) % gsz); u.pn = (wgid % nig) / gsz; return true;
.LBB0_569:
	s_or_b64 exec, exec, s[2:3]
	s_mov_b32 s1, s69
	s_waitcnt lgkmcnt(0)
	s_waitcnt vmcnt(0)
	s_barrier
	s_ashr_i32 s13, s1, 31
	s_cmpk_lt_i32 s1, 0x580
	s_cselect_b64 s[2:3], -1, 0
	s_cmpk_gt_i32 s1, 0x57f
	s_mov_b32 s22, -1
	s_cbranch_scc1 .LBB0_571
	s_lshr_b32 s4, s13, 29
	s_add_i32 s4, s1, s4
	s_ashr_i32 s12, s4, 3
	s_and_b32 s4, s4, -8
	s_sub_i32 s4, s1, s4
	s_cmp_lt_i32 s4, 0
	s_movk_i32 s16, 0xb1
	s_cselect_b32 s16, s16, 0xb0
	s_mul_i32 s4, s4, s16
	s_add_i32 s4, s4, s12
	s_mul_hi_i32 s12, s4, 0x2e8ba2e9
	s_lshr_b32 s16, s12, 31
	s_ashr_i32 s12, s12, 5
	s_add_i32 s12, s12, s16
	s_lshl_b32 s16, s12, 3
	s_mulk_i32 s12, 0xb0
	s_sub_i32 s4, s4, s12
	s_bfe_u32 s12, s4, 0x3001c
	s_add_i32 s12, s4, s12
	s_and_b32 s12, s12, 0xfff8
	s_sub_i32 s4, s4, s12
	s_sext_i32_i16 s4, s4
	s_add_i32 s22, s16, s4

; __device__ __forceinline__ unsigned xb_add(unsigned* p, unsigned v) { return __hip_atomic_fetch_add(p, v, __ATOMIC_RELAXED, __HIP_MEMORY_SCOPE_AGENT); }
; __device__ __forceinline__ void xcd_barrier(const XcdBarrier& b) {
;     asm volatile("s_waitcnt vmcnt(0)" ::: "memory");
;     __syncthreads();
;     if (threadIdx.x == 0) {
;         unsigned* bar = b.bar;
;         __builtin_amdgcn_s_waitcnt(0);
;         unsigned nloc = b.st[0], nx = b.st[1];
;         if (nloc == 0u) { xcd_barrier_complete(bar, b.x, nloc, nx); b.st[0] = nloc; b.st[1] = nx; }
;         const unsigned old = xb_add(&bar[XB_XSUB(b.x)], 1u);
;         const unsigned gen = old / nloc;
;         if (old + 1u == (gen + 1u) * nloc) {
.LBB0_628:
	s_waitcnt vmcnt(0)
	s_waitcnt vmcnt(0)
	s_barrier
	s_cmp_lg_u32 s98, 0
	s_cbranch_scc0 .Lpf_skip_680
	v_readlane_b32 s101, v253, 38
	v_readlane_b32 s12, v255, 45
	v_readlane_b32 s13, v255, 46
	s_nop 3
	s_sub_u32 s101, s101, 1
	s_cmp_gt_u32 s101, 3
	s_cbranch_scc1 .Lpf_skip_680
	v_and_b32_e32 v140, 63, v244
	v_lshl_add_u32 v140, s101, 6, v140
	v_mul_u32_u24_e32 v140, 0x1600, v140
	v_readlane_b32 s101, v253, 1
	s_add_u32 s12, s12, 0x2100000
	s_addc_u32 s13, s13, 0
	s_nop 1
	s_lshr_b32 s101, s101, 6
	s_mul_i32 s101, s101, 0x160000
	s_add_u32 s12, s12, s101
	s_addc_u32 s13, s13, 0
	global_load_dword v141, v140, s[12:13]
	global_load_dword v141, v140, s[12:13] offset:64
	global_load_dword v141, v140, s[12:13] offset:128
	global_load_dword v141, v140, s[12:13] offset:192
	global_load_dword v141, v140, s[12:13] offset:256
	global_load_dword v141, v140, s[12:13] offset:320
	global_load_dword v141, v140, s[12:13] offset:384
	global_load_dword v141, v140, s[12:13] offset:448
.Lpf_skip_680:
	s_mov_b64 s[16:17], exec
	v_readlane_b32 s12, v253, 36
	v_readlane_b32 s13, v253, 37
	s_and_b64 s[12:13], s[16:17], s[12:13]
	s_mov_b64 exec, s[12:13]
	s_cbranch_execz .LBB0_680
	s_cmp_lg_u32 s98, 0
	s_cbranch_scc0 .Lgb_full_680
	v_readlane_b32 s4, v253, 1
	v_readlane_b32 s12, v253, 56
	v_readlane_b32 s13, v253, 57
	s_add_i32 s99, s99, 4
	s_nop 2
	s_and_b32 s4, s4, 63
	s_lshl_b32 s4, s4, 7
	s_add_i32 s4, s4, 0x3e00
	v_mov_b32_e32 v2, s4
	s_mov_b32 s1, 0
	s_nop 1
	global_atomic_add v5, v2, v234, s[12:13] sc0
	v_mov_b32_e32 v4, 0x5ec0
	global_atomic_add v4, v234, s[12:13]
	s_waitcnt vmcnt(1)
	v_readfirstlane_b32 s4, v5
	s_nop 3
	s_add_i32 s4, s4, 1
	s_cmp_ge_u32 s4, s99
	s_cbranch_scc1 .Lgb_grp_ok_680

;     __host__ __device__ bool next(int i, Unit& u) const {
;         const long L = (long)i * G + c; if (L >= nwg) return false;
;         int wgid = (int)L; { const int q = nwg / NXCD, r = nwg % NXCD, xcd = wgid % NXCD, off = wgid / NXCD; wgid = (xcd < r ? xcd * (q + 1) : r * (q + 1) + (xcd - r) * q) + off; }
;         const int nig = WGM * nN, gid = wgid / nig, fm = gid * WGM, gsz = (nM - fm) < WGM ? (nM - fm) : WGM;
;         u.pm = fm + ((wgid % nig) % gsz); u.pn = (wgid % nig) / gsz; return true;
; __device__ __forceinline__ void xcd_barrier(const XcdBarrier& b) {
;     ...
;             __builtin_amdgcn_fence(__ATOMIC_ACQUIRE, "agent");
;             asm volatile("s_waitcnt vmcnt(0)" ::: "memory");
;         }
;     }
;     __syncthreads();
; }
.LBB0_680:
	s_or_b64 exec, exec, s[16:17]
	s_mov_b32 s1, s69
	s_waitcnt lgkmcnt(0)
	v_mov_b32_e32 v2, v244
	s_waitcnt vmcnt(0)
	s_barrier
	s_cmpk_lt_i32 s1, 0x100
	v_readfirstlane_b32 s12, v2
	s_cbranch_scc0 .LBB0_708
	s_ashr_i32 s3, s1, 31
	s_lshr_b32 s4, s3, 29
	s_add_i32 s13, s1, s4
	s_and_b32 s4, s13, -8
	s_sub_i32 s4, s1, s4
	s_cmp_gt_i32 s4, -1
	s_mov_b64 s[16:17], -1
	s_cbranch_scc0 .LBB0_683
	s_lshl_b32 s19, s4, 5
	s_mov_b64 s[16:17], 0

; __device__ __forceinline__ unsigned xb_add(unsigned* p, unsigned v) { return __hip_atomic_fetch_add(p, v, __ATOMIC_RELAXED, __HIP_MEMORY_SCOPE_AGENT); }
; __device__ __forceinline__ void xcd_barrier(const XcdBarrier& b) {
;     asm volatile("s_waitcnt vmcnt(0)" ::: "memory");
;     __syncthreads();
;     if (threadIdx.x == 0) {
;         unsigned* bar = b.bar;
;         __builtin_amdgcn_s_waitcnt(0);
;         unsigned nloc = b.st[0], nx = b.st[1];
;         if (nloc == 0u) { xcd_barrier_complete(bar, b.x, nloc, nx); b.st[0] = nloc; b.st[1] = nx; }
;         const unsigned old = xb_add(&bar[XB_XSUB(b.x)], 1u);
;         const unsigned gen = old / nloc;
;         if (old + 1u == (gen + 1u) * nloc) {
.LBB0_708:
	s_waitcnt vmcnt(0)
	s_barrier
	s_cmp_lg_u32 s98, 0
	s_cbranch_scc0 .Lpf_skip_137
	s_cmp_eq_u32 s92, 3
	s_cbranch_scc1 .Lpf_skip_137
	v_readlane_b32 s101, v253, 38
	v_readlane_b32 s12, v255, 45
	v_readlane_b32 s13, v255, 46
	s_nop 3
	s_sub_u32 s101, s101, 1
	s_cmp_gt_u32 s101, 3
	s_cbranch_scc1 .Lpf_skip_137
	v_and_b32_e32 v140, 63, v244
	v_lshl_add_u32 v140, s101, 6, v140
	v_mul_u32_u24_e32 v140, 0x800, v140
	v_readlane_b32 s101, v253, 1
	s_add_u32 s12, s12, 0x2680000
	s_addc_u32 s13, s13, 0
	s_nop 1
	s_lshr_b32 s101, s101, 6
	s_mul_i32 s101, s101, 0x80000
	s_add_u32 s12, s12, s101
	s_addc_u32 s13, s13, 0
	global_load_dword v141, v140, s[12:13]
	global_load_dword v141, v140, s[12:13] offset:64
	global_load_dword v141, v140, s[12:13] offset:128
	global_load_dword v141, v140, s[12:13] offset:192
	global_load_dword v141, v140, s[12:13] offset:256
	global_load_dword v141, v140, s[12:13] offset:320
	global_load_dword v141, v140, s[12:13] offset:384
	global_load_dword v141, v140, s[12:13] offset:448
.Lpf_skip_137:
	s_mov_b64 s[16:17], exec
	v_readlane_b32 s12, v253, 36
	v_readlane_b32 s13, v253, 37
	s_and_b64 s[12:13], s[16:17], s[12:13]
	s_mov_b64 exec, s[12:13]
	s_cbranch_execz .LBB0_137
	s_cmp_lg_u32 s98, 0
	s_cbranch_scc0 .Lgb_full_137
	v_readlane_b32 s4, v253, 1
	v_readlane_b32 s12, v253, 56
	v_readlane_b32 s13, v253, 57
	s_add_i32 s99, s99, 4
	s_nop 2
	s_and_b32 s4, s4, 63
	s_lshl_b32 s4, s4, 7
	s_add_i32 s4, s4, 0x3e00
	v_mov_b32_e32 v2, s4
	s_mov_b32 s1, 0
	s_nop 1
	global_atomic_add v5, v2, v234, s[12:13] sc0
	v_mov_b32_e32 v4, 0x5e80
	global_atomic_add v4, v234, s[12:13]
	v_mov_b32_e32 v7, 0x5ec0
	global_load_dword v6, v7, s[12:13] sc1
	s_waitcnt vmcnt(2)
	v_readfirstlane_b32 s4, v5
	s_nop 3
	s_add_i32 s4, s4, 1
	s_cmp_ge_u32 s4, s99
	s_cbranch_scc1 .Lgb_grp_ok_137
